# P0 rmsnorm row sums via DPP adds + v_permlane16/32_swap instead of six dependent ds_bpermute per row (on top of v72)
# speedup vs baseline: 1.0117x; 1.0043x over previous
; #define P0_LOADROW(buf, mm) do { const int m_ = (mm); if (m_ < M) { const float* xr_ = m_ < MP ? P.x_p + (size_t)m_ * 1024 : P.x_s + (size_t)(m_ - MP) * 1024; \
;         _Pragma("unroll") for (int j = 0; j < 4; ++j) buf[j] = ((const f32x4*)xr_)[64 * j + lane]; } } while (0)
; __device__ __forceinline__ void phase0(const Params& P, LAS unsigned char* lds, int tid, int lane, int wave, int G) {
;     ...
;     P0_LOADROW(rb0, gw); P0_LOADROW(rb1, gw + NGW); P0_LOADROW(rb2, gw + 2 * NGW);
;     for (int m = gw; m < M; m += 3 * NGW) {
;         P0_DOROW(rb0, m);           P0_LOADROW(rb0, m + 3 * NGW);
;         P0_DOROW(rb1, m + NGW);     P0_LOADROW(rb1, m + 4 * NGW);
;         P0_DOROW(rb2, m + 2 * NGW); P0_LOADROW(rb2, m + 5 * NGW);
.LBB0_54:
	s_waitcnt vmcnt(3)
	v_pk_mul_f32 v[84:85], v[20:21], v[20:21]
	v_pk_mul_f32 v[86:87], v[18:19], v[18:19]
	s_waitcnt vmcnt(2)
	v_pk_mul_f32 v[80:81], v[24:25], v[24:25]
	v_pk_mul_f32 v[82:83], v[22:23], v[22:23]
	v_pk_mov_b32 v[88:89], v[86:87], v[84:85] op_sel:[1,0]
	v_mov_b32_e32 v87, v85
	v_pk_add_f32 v[84:85], v[88:89], v[86:87]
	v_pk_mov_b32 v[86:87], v[82:83], v[80:81] op_sel:[1,0]
	v_mov_b32_e32 v83, v81
	v_pk_add_f32 v[80:81], v[86:87], v[82:83]
	v_pk_add_f32 v[84:85], v[84:85], v[84:85] op_sel_hi:[0,1]
	v_pk_add_f32 v[80:81], v[80:81], v[80:81] op_sel_hi:[0,1]
	s_waitcnt vmcnt(1)
	v_mul_f32_e32 v80, v26, v26
	v_pk_fma_f32 v[82:83], v[26:27], v[26:27], v[80:81] op_sel_hi:[1,1,0]
	v_mul_f32_e32 v80, v28, v28
	v_pk_fma_f32 v[86:87], v[28:29], v[28:29], v[80:81] op_sel_hi:[1,1,0]
	s_waitcnt vmcnt(0)
	v_mul_f32_e32 v82, v30, v30
	v_mul_f32_e32 v86, v31, v31
	v_mul_f32_e32 v84, v32, v32
	v_mul_f32_e32 v80, v33, v33
	v_pk_add_f32 v[82:83], v[82:83], v[86:87]
	v_pk_add_f32 v[80:81], v[84:85], v[80:81]
	s_add_i32 s7, s30, s34
	v_pk_add_f32 v[80:81], v[82:83], v[80:81]
	s_cmp_lt_i32 s7, 0x10100
	v_add_f32_e32 v79, v80, v81
	s_waitcnt lgkmcnt(0)
	s_nop 1
	v_add_f32_dpp v79, v79, v79 quad_perm:[1,0,3,2] row_mask:0xf bank_mask:0xf
	s_nop 1
	v_add_f32_dpp v79, v79, v79 quad_perm:[2,3,0,1] row_mask:0xf bank_mask:0xf
	s_nop 1
	v_add_f32_dpp v79, v79, v79 row_half_mirror row_mask:0xf bank_mask:0xf
	s_nop 1
	v_add_f32_dpp v79, v79, v79 row_mirror row_mask:0xf bank_mask:0xf
	v_mov_b32_e32 v80, v79
	s_nop 1
	v_permlane16_swap_b32_e32 v79, v80
	v_add_f32_e32 v79, v79, v80
	v_mov_b32_e32 v80, v79
	s_nop 1
	v_permlane32_swap_b32_e32 v79, v80
	v_add_f32_e32 v79, v79, v80
	v_fmamk_f32 v79, v79, 0x3a800000, v69
	v_rsq_f32_e32 v80, v79
	s_nop 0
	v_pk_mul_f32 v[82:83], v[18:19], v[80:81] op_sel_hi:[1,0]
	v_pk_mul_f32 v[84:85], v[20:21], v[80:81] op_sel_hi:[1,0]
	v_pk_mul_f32 v[86:87], v[22:23], v[80:81] op_sel_hi:[1,0]
	v_pk_mul_f32 v[88:89], v[24:25], v[80:81] op_sel_hi:[1,0]
	v_pk_mul_f32 v[84:85], v[4:5], v[84:85]
	v_pk_mul_f32 v[82:83], v[2:3], v[82:83]
	v_pk_mul_f32 v[88:89], v[8:9], v[88:89]
	v_pk_mul_f32 v[86:87], v[6:7], v[86:87]
	v_cvt_pk_bf16_f32 v82, v82, v83
	v_cvt_pk_bf16_f32 v83, v84, v85
	v_pk_mul_f32 v[90:91], v[26:27], v[80:81] op_sel_hi:[1,0]
	v_cvt_pk_bf16_f32 v84, v86, v87
	v_cvt_pk_bf16_f32 v85, v88, v89
	global_store_dwordx2 v[72:73], v[82:83], off
	global_store_dwordx2 v[72:73], v[84:85], off offset:512
	v_pk_mul_f32 v[82:83], v[28:29], v[80:81] op_sel_hi:[1,0]
	v_pk_mul_f32 v[84:85], v[10:11], v[90:91]
	v_pk_mul_f32 v[82:83], v[12:13], v[82:83]
	v_cvt_pk_bf16_f32 v84, v84, v85
	v_cvt_pk_bf16_f32 v85, v82, v83
	v_pk_mul_f32 v[82:83], v[30:31], v[80:81] op_sel_hi:[1,0]
	v_pk_mul_f32 v[80:81], v[32:33], v[80:81] op_sel_hi:[1,0]
	v_pk_mul_f32 v[82:83], v[14:15], v[82:83]
	v_pk_mul_f32 v[80:81], v[16:17], v[80:81]
	v_cvt_pk_bf16_f32 v82, v82, v83
	v_cvt_pk_bf16_f32 v83, v80, v81
	global_store_dwordx2 v[72:73], v[84:85], off offset:1024
	global_store_dwordx2 v[72:73], v[82:83], off offset:1536
	s_cbranch_scc0 .LBB0_59
	s_add_i32 s10, s7, 0xffff0000
	s_cmp_lt_i32 s7, 0x10000
	s_cselect_b32 s11, s35, 0
	s_cselect_b32 s10, s31, s10
	s_cselect_b32 s7, s69, s71
	s_cselect_b32 s12, s68, s70
	s_lshl_b64 s[10:11], s[10:11], 12
	s_add_u32 s10, s12, s10
	s_addc_u32 s11, s7, s11
	global_load_dwordx4 v[18:21], v1, s[10:11] nt
	global_load_dwordx4 v[22:25], v1, s[10:11] offset:1024 nt
	global_load_dwordx4 v[26:29], v1, s[10:11] offset:2048 nt
	global_load_dwordx4 v[30:33], v1, s[10:11] offset:3072 nt
	s_add_i32 s10, s26, s34
	s_cmp_gt_i32 s10, 0x100ff
	s_cbranch_scc0 .LBB0_60

; #define P0_LOADROW(buf, mm) do { const int m_ = (mm); if (m_ < M) { const float* xr_ = m_ < MP ? P.x_p + (size_t)m_ * 1024 : P.x_s + (size_t)(m_ - MP) * 1024; \
;         _Pragma("unroll") for (int j = 0; j < 4; ++j) buf[j] = ((const f32x4*)xr_)[64 * j + lane]; } } while (0)
; __device__ __forceinline__ void phase0(const Params& P, LAS unsigned char* lds, int tid, int lane, int wave, int G) {
;     ...
;     P0_LOADROW(rb0, gw); P0_LOADROW(rb1, gw + NGW); P0_LOADROW(rb2, gw + 2 * NGW);
;     for (int m = gw; m < M; m += 3 * NGW) {
;         P0_DOROW(rb0, m);           P0_LOADROW(rb0, m + 3 * NGW);
;         P0_DOROW(rb1, m + NGW);     P0_LOADROW(rb1, m + 4 * NGW);
;         P0_DOROW(rb2, m + 2 * NGW); P0_LOADROW(rb2, m + 5 * NGW);
.LBB0_60:
	v_pk_mul_f32 v[80:81], v[36:37], v[36:37]
	v_pk_mul_f32 v[82:83], v[34:35], v[34:35]
	s_ashr_i32 s11, s10, 31
	v_pk_mov_b32 v[84:85], v[82:83], v[80:81] op_sel:[1,0]
	v_mov_b32_e32 v83, v81
	v_pk_add_f32 v[80:81], v[84:85], v[82:83]
	v_pk_mul_f32 v[82:83], v[40:41], v[40:41]
	v_pk_add_f32 v[80:81], v[80:81], v[80:81] op_sel_hi:[0,1]
	v_pk_mul_f32 v[84:85], v[38:39], v[38:39]
	v_mul_f32_e32 v80, v42, v42
	v_pk_mov_b32 v[86:87], v[84:85], v[82:83] op_sel:[1,0]
	v_mov_b32_e32 v85, v83
	v_pk_add_f32 v[82:83], v[86:87], v[84:85]
	v_pk_fma_f32 v[84:85], v[42:43], v[42:43], v[80:81] op_sel_hi:[1,1,0]
	v_mul_f32_e32 v80, v44, v44
	v_pk_add_f32 v[82:83], v[82:83], v[82:83] op_sel_hi:[0,1]
	v_pk_fma_f32 v[86:87], v[44:45], v[44:45], v[80:81] op_sel_hi:[1,1,0]
	v_mul_f32_e32 v84, v46, v46
	v_mul_f32_e32 v86, v47, v47
	v_mul_f32_e32 v82, v48, v48
	v_mul_f32_e32 v80, v49, v49
	v_pk_add_f32 v[84:85], v[84:85], v[86:87]
	v_pk_add_f32 v[80:81], v[82:83], v[80:81]
	s_lshl_b64 s[10:11], s[10:11], 11
	v_pk_add_f32 v[80:81], v[84:85], v[80:81]
	v_lshl_add_u64 v[82:83], v[70:71], 0, s[10:11]
	v_add_f32_e32 v79, v80, v81
	s_waitcnt lgkmcnt(0)
	s_nop 1
	v_add_f32_dpp v79, v79, v79 quad_perm:[1,0,3,2] row_mask:0xf bank_mask:0xf
	s_nop 1
	v_add_f32_dpp v79, v79, v79 quad_perm:[2,3,0,1] row_mask:0xf bank_mask:0xf
	s_nop 1
	v_add_f32_dpp v79, v79, v79 row_half_mirror row_mask:0xf bank_mask:0xf
	s_nop 1
	v_add_f32_dpp v79, v79, v79 row_mirror row_mask:0xf bank_mask:0xf
	v_mov_b32_e32 v80, v79
	s_nop 1
	v_permlane16_swap_b32_e32 v79, v80
	v_add_f32_e32 v79, v79, v80
	v_mov_b32_e32 v80, v79
	s_nop 1
	v_permlane32_swap_b32_e32 v79, v80
	v_add_f32_e32 v79, v79, v80
	v_fmamk_f32 v79, v79, 0x3a800000, v69
	v_rsq_f32_e32 v80, v79
	s_nop 0
	v_pk_mul_f32 v[84:85], v[34:35], v[80:81] op_sel_hi:[1,0]
	v_pk_mul_f32 v[86:87], v[36:37], v[80:81] op_sel_hi:[1,0]
	v_pk_mul_f32 v[88:89], v[38:39], v[80:81] op_sel_hi:[1,0]
	v_pk_mul_f32 v[90:91], v[40:41], v[80:81] op_sel_hi:[1,0]
	v_pk_mul_f32 v[86:87], v[4:5], v[86:87]
	v_pk_mul_f32 v[84:85], v[2:3], v[84:85]
	v_pk_mul_f32 v[90:91], v[8:9], v[90:91]
	v_pk_mul_f32 v[88:89], v[6:7], v[88:89]
	v_cvt_pk_bf16_f32 v84, v84, v85
	v_cvt_pk_bf16_f32 v85, v86, v87
	v_cvt_pk_bf16_f32 v86, v88, v89
	v_cvt_pk_bf16_f32 v87, v90, v91
	global_store_dwordx2 v[82:83], v[84:85], off
	global_store_dwordx2 v[82:83], v[86:87], off offset:512
	v_pk_mul_f32 v[84:85], v[42:43], v[80:81] op_sel_hi:[1,0]
	v_pk_mul_f32 v[86:87], v[44:45], v[80:81] op_sel_hi:[1,0]
	v_pk_mul_f32 v[84:85], v[10:11], v[84:85]
	v_pk_mul_f32 v[86:87], v[12:13], v[86:87]
	v_cvt_pk_bf16_f32 v84, v84, v85
	v_cvt_pk_bf16_f32 v85, v86, v87
	global_store_dwordx2 v[82:83], v[84:85], off offset:1024
	v_pk_mul_f32 v[84:85], v[46:47], v[80:81] op_sel_hi:[1,0]
	v_pk_mul_f32 v[80:81], v[48:49], v[80:81] op_sel_hi:[1,0]
	v_pk_mul_f32 v[84:85], v[14:15], v[84:85]
	v_pk_mul_f32 v[80:81], v[16:17], v[80:81]
	v_cvt_pk_bf16_f32 v84, v84, v85
	v_cvt_pk_bf16_f32 v85, v80, v81
	global_store_dwordx2 v[82:83], v[84:85], off offset:1536
	s_add_i32 s7, s27, s34
	s_cmp_gt_i32 s7, 0x100ff
	s_cbranch_scc0 .LBB0_57

; #define P0_LOADROW(buf, mm) do { const int m_ = (mm); if (m_ < M) { const float* xr_ = m_ < MP ? P.x_p + (size_t)m_ * 1024 : P.x_s + (size_t)(m_ - MP) * 1024; \
;         _Pragma("unroll") for (int j = 0; j < 4; ++j) buf[j] = ((const f32x4*)xr_)[64 * j + lane]; } } while (0)
; __device__ __forceinline__ void phase0(const Params& P, LAS unsigned char* lds, int tid, int lane, int wave, int G) {
;     ...
;     P0_LOADROW(rb0, gw); P0_LOADROW(rb1, gw + NGW); P0_LOADROW(rb2, gw + 2 * NGW);
;     for (int m = gw; m < M; m += 3 * NGW) {
;         P0_DOROW(rb0, m);           P0_LOADROW(rb0, m + 3 * NGW);
;         P0_DOROW(rb1, m + NGW);     P0_LOADROW(rb1, m + 4 * NGW);
;         P0_DOROW(rb2, m + 2 * NGW); P0_LOADROW(rb2, m + 5 * NGW);
.LBB0_62:
	v_pk_mul_f32 v[80:81], v[52:53], v[52:53]
	v_pk_mul_f32 v[82:83], v[50:51], v[50:51]
	s_ashr_i32 s11, s10, 31
	v_pk_mov_b32 v[84:85], v[82:83], v[80:81] op_sel:[1,0]
	v_mov_b32_e32 v83, v81
	v_pk_add_f32 v[80:81], v[84:85], v[82:83]
	v_pk_mul_f32 v[82:83], v[56:57], v[56:57]
	v_pk_add_f32 v[80:81], v[80:81], v[80:81] op_sel_hi:[0,1]
	v_pk_mul_f32 v[84:85], v[54:55], v[54:55]
	v_mul_f32_e32 v80, v58, v58
	v_pk_mov_b32 v[86:87], v[84:85], v[82:83] op_sel:[1,0]
	v_mov_b32_e32 v85, v83
	v_pk_add_f32 v[82:83], v[86:87], v[84:85]
	v_pk_fma_f32 v[84:85], v[58:59], v[58:59], v[80:81] op_sel_hi:[1,1,0]
	v_mul_f32_e32 v80, v60, v60
	v_pk_add_f32 v[82:83], v[82:83], v[82:83] op_sel_hi:[0,1]
	v_pk_fma_f32 v[86:87], v[60:61], v[60:61], v[80:81] op_sel_hi:[1,1,0]
	v_mul_f32_e32 v84, v62, v62
	v_mul_f32_e32 v86, v63, v63
	v_mul_f32_e32 v82, v64, v64
	v_mul_f32_e32 v80, v65, v65
	v_pk_add_f32 v[84:85], v[84:85], v[86:87]
	v_pk_add_f32 v[80:81], v[82:83], v[80:81]
	s_lshl_b64 s[10:11], s[10:11], 11
	v_pk_add_f32 v[80:81], v[84:85], v[80:81]
	v_lshl_add_u64 v[82:83], v[70:71], 0, s[10:11]
	v_add_f32_e32 v79, v80, v81
	s_waitcnt lgkmcnt(0)
	s_nop 1
	v_add_f32_dpp v79, v79, v79 quad_perm:[1,0,3,2] row_mask:0xf bank_mask:0xf
	s_nop 1
	v_add_f32_dpp v79, v79, v79 quad_perm:[2,3,0,1] row_mask:0xf bank_mask:0xf
	s_nop 1
	v_add_f32_dpp v79, v79, v79 row_half_mirror row_mask:0xf bank_mask:0xf
	s_nop 1
	v_add_f32_dpp v79, v79, v79 row_mirror row_mask:0xf bank_mask:0xf
	v_mov_b32_e32 v80, v79
	s_nop 1
	v_permlane16_swap_b32_e32 v79, v80
	v_add_f32_e32 v79, v79, v80
	v_mov_b32_e32 v80, v79
	s_nop 1
	v_permlane32_swap_b32_e32 v79, v80
	v_add_f32_e32 v79, v79, v80
	v_fmamk_f32 v79, v79, 0x3a800000, v69
	v_rsq_f32_e32 v80, v79
	s_nop 0
	v_pk_mul_f32 v[84:85], v[50:51], v[80:81] op_sel_hi:[1,0]
	v_pk_mul_f32 v[86:87], v[52:53], v[80:81] op_sel_hi:[1,0]
	v_pk_mul_f32 v[88:89], v[54:55], v[80:81] op_sel_hi:[1,0]
	v_pk_mul_f32 v[90:91], v[56:57], v[80:81] op_sel_hi:[1,0]
	v_pk_mul_f32 v[86:87], v[4:5], v[86:87]
	v_pk_mul_f32 v[84:85], v[2:3], v[84:85]
	v_pk_mul_f32 v[90:91], v[8:9], v[90:91]
	v_pk_mul_f32 v[88:89], v[6:7], v[88:89]
	v_cvt_pk_bf16_f32 v84, v84, v85
	v_cvt_pk_bf16_f32 v85, v86, v87
	v_cvt_pk_bf16_f32 v86, v88, v89
	v_cvt_pk_bf16_f32 v87, v90, v91
	global_store_dwordx2 v[82:83], v[84:85], off
	global_store_dwordx2 v[82:83], v[86:87], off offset:512
	v_pk_mul_f32 v[84:85], v[58:59], v[80:81] op_sel_hi:[1,0]
	v_pk_mul_f32 v[86:87], v[60:61], v[80:81] op_sel_hi:[1,0]
	v_pk_mul_f32 v[84:85], v[10:11], v[84:85]
	v_pk_mul_f32 v[86:87], v[12:13], v[86:87]
	v_cvt_pk_bf16_f32 v84, v84, v85
	v_cvt_pk_bf16_f32 v85, v86, v87
	global_store_dwordx2 v[82:83], v[84:85], off offset:1024
	v_pk_mul_f32 v[84:85], v[62:63], v[80:81] op_sel_hi:[1,0]
	v_pk_mul_f32 v[80:81], v[64:65], v[80:81] op_sel_hi:[1,0]
	v_pk_mul_f32 v[84:85], v[14:15], v[84:85]
	v_pk_mul_f32 v[80:81], v[16:17], v[80:81]
	v_cvt_pk_bf16_f32 v84, v84, v85
	v_cvt_pk_bf16_f32 v85, v80, v81
	global_store_dwordx2 v[82:83], v[84:85], off offset:1536
	s_add_i32 s7, s29, s34
	s_cmp_gt_i32 s7, 0x100ff
	s_cbranch_scc1 .LBB0_53
